# attention loops: last scale pair packed, redundant nops after scalar moves removed
# speedup vs baseline: 1.0034x; 1.0022x over previous
; __device__ __forceinline__ void partialSM(f32x16& p0, f32x16& p1, float& m_reg, float& mn, float& alpha, float C, float thrRaw) {
;     ...
;   float mnC = -mn * C;
; #pragma unroll
;   for (int r = 0; r < 16; ++r) p0[r] = fmaf(p0[r], C, mnC);
; #pragma unroll
;   for (int r = 0; r < 16; ++r) p1[r] = fmaf(p1[r], C, mnC);
; #pragma unroll
;   for (int r = 0; r < 16; ++r) p0[r] = __builtin_amdgcn_exp2f(p0[r]);
.LBB0_670:
	v_cndmask_b32_e64 v134, v131, v215, s[2:3]
	v_mul_f32_e32 v120, 0xbe0293ee, v134
	s_mov_b32 s2, 0x3e0293ee
	v_pk_fma_f32 v[82:83], v[82:83], s[2:3], v[120:121] op_sel_hi:[1,0,0]
	v_pk_fma_f32 v[84:85], v[84:85], s[2:3], v[120:121] op_sel_hi:[1,0,0]
	v_pk_fma_f32 v[86:87], v[86:87], s[2:3], v[120:121] op_sel_hi:[1,0,0]
	v_pk_fma_f32 v[88:89], v[88:89], s[2:3], v[120:121] op_sel_hi:[1,0,0]
	v_pk_fma_f32 v[90:91], v[90:91], s[2:3], v[120:121] op_sel_hi:[1,0,0]
	v_pk_fma_f32 v[92:93], v[92:93], s[2:3], v[120:121] op_sel_hi:[1,0,0]
	v_pk_fma_f32 v[94:95], v[94:95], s[2:3], v[120:121] op_sel_hi:[1,0,0]
	v_pk_fma_f32 v[96:97], v[96:97], s[2:3], v[120:121] op_sel_hi:[1,0,0]
	s_mov_b32 s2, 0x3e0293ee
	v_exp_f32_e32 v145, v82
	v_exp_f32_e32 v216, v83
	v_exp_f32_e32 v131, v84
	v_exp_f32_e32 v215, v85
	v_exp_f32_e32 v132, v86
	v_exp_f32_e32 v144, v87
	v_exp_f32_e32 v133, v88
	v_exp_f32_e32 v143, v89
	v_exp_f32_e32 v140, v90
	v_exp_f32_e32 v142, v91
	v_exp_f32_e32 v139, v92
	v_exp_f32_e32 v141, v93
	v_exp_f32_e32 v136, v94
	v_exp_f32_e32 v138, v95
	v_exp_f32_e32 v135, v96
	v_exp_f32_e32 v137, v97
	v_pk_fma_f32 v[126:127], v[66:67], s[2:3], v[120:121] op_sel_hi:[1,0,0]
	v_pk_fma_f32 v[124:125], v[68:69], s[2:3], v[120:121] op_sel_hi:[1,0,0]
	v_pk_fma_f32 v[118:119], v[70:71], s[2:3], v[120:121] op_sel_hi:[1,0,0]
	v_pk_fma_f32 v[116:117], v[72:73], s[2:3], v[120:121] op_sel_hi:[1,0,0]
	v_pk_fma_f32 v[114:115], v[74:75], s[2:3], v[120:121] op_sel_hi:[1,0,0]
	v_pk_fma_f32 v[128:129], v[76:77], s[2:3], v[120:121] op_sel_hi:[1,0,0]
	v_pk_fma_f32 v[122:123], v[78:79], s[2:3], v[120:121] op_sel_hi:[1,0,0]
	v_pk_fma_f32 v[120:121], v[80:81], s[2:3], v[120:121] op_sel_hi:[1,0,0]
	v_fma_f32 v66, v211, v150, v212
	s_mov_b64 s[2:3], 0x140000
	v_fma_f32 v150, v66, v214, v217
	v_lshl_add_u64 v[146:147], v[146:147], 0, s[2:3]
	s_and_b64 vcc, exec, s[4:5]
	s_waitcnt lgkmcnt(0)
	s_barrier
	s_cbranch_vccnz .LBB0_672
	v_mov_b32_e32 v211, v130
	ds_write_b128 v209, v[244:247] offset:16384
	ds_write_b128 v210, v[194:197] offset:16384
	s_branch .LBB0_660

; #define SBAR() __builtin_amdgcn_sched_barrier(0)
; __device__ __forceinline__ void finishSM(f32x16& p0, f32x16& p1, float alpha, float& l_reg, bf16x8& pa0, bf16x8& pa1, bf16x8& pa2, bf16x8& pa3) {
; #pragma unroll
;   for (int r = 0; r < 16; ++r) p1[r] = __builtin_amdgcn_exp2f(p1[r]);
;   float ps = 0;
; #pragma unroll
;   for (int r = 0; r < 16; ++r) ps += p0[r];
; #pragma unroll
;   for (int r = 0; r < 16; ++r) ps += p1[r];
;   { auto rr = __builtin_amdgcn_permlane32_swap(__float_as_uint(ps), __float_as_uint(ps), false, false);
;     ps = __uint_as_float(rr[0]) + __uint_as_float(rr[1]); }
;   l_reg = l_reg * alpha + ps;
;     ...
;   PK4(p0, 0, pa0); PK4(p0, 8, pa1); PK4(p1, 0, pa2); PK4(p1, 8, pa3);
;     ...
; }
; template <int DK, bool QL>
; __device__ __forceinline__ void qkt(f32x16& p0, f32x16& p1, const bf16* Ks, const bf16x8* qr, const char* ql, int r32, int hi) {
;   p0 = f32x16{}; p1 = f32x16{};
; #pragma unroll
;   for (int d0 = 0; d0 < DK / 16; ++d0) { int cb = (d0 * 16 + hi * 8) * 2;
;     const bf16x8 qv = QL ? *reinterpret_cast<const bf16x8*>(ql + d0 * 1024) : qr[d0];
;     bf16x8 b0 = *reinterpret_cast<const bf16x8*>((const char*)Ks + kswz<DK>(r32, cb));
;     bf16x8 b1 = *reinterpret_cast<const bf16x8*>((const char*)Ks + kswz<DK>(32 + r32, cb));
;     p0 = __builtin_amdgcn_mfma_f32_32x32x16_bf16(b0, qv, p0, 0, 0, 0);
;     p1 = __builtin_amdgcn_mfma_f32_32x32x16_bf16(b1, qv, p1, 0, 0, 0); }
; }
; template <int OFF> __device__ __forceinline__ s16x4 tr_read(int vb) {
;   s16x4 r; asm volatile("ds_read_b64_tr_b16 %0, %1 offset:%2" : "=&v"(r) : "v"(vb), "i"(OFF) : "memory"); return r;
; }
; template <int D0> __device__ __forceinline__ void pv_one(f32x16& od, int vb, bf16x8 pa0, bf16x8 pa1, bf16x8 pa2, bf16x8 pa3) {
;   const s16x4 l0 = tr_read<v_rd_off(D0, 0, 0)>(vb), h0 = tr_read<v_rd_off(D0, 0, 1)>(vb), l1 = tr_read<v_rd_off(D0, 1, 0)>(vb), h1 = tr_read<v_rd_off(D0, 1, 1)>(vb);
;   const s16x4 l2 = tr_read<v_rd_off(D0, 2, 0)>(vb), h2 = tr_read<v_rd_off(D0, 2, 1)>(vb), l3 = tr_read<v_rd_off(D0, 3, 0)>(vb), h3 = tr_read<v_rd_off(D0, 3, 1)>(vb);
;   asm volatile("s_waitcnt lgkmcnt(0)" ::: "memory"); SBAR();
;     ...
;   od = __builtin_amdgcn_mfma_f32_32x32x16_bf16(pa0, PK(l0, h0), od, 0, 0, 0);
;   od = __builtin_amdgcn_mfma_f32_32x32x16_bf16(pa1, PK(l1, h1), od, 0, 0, 0);
;   od = __builtin_amdgcn_mfma_f32_32x32x16_bf16(pa2, PK(l2, h2), od, 0, 0, 0);
.LBB0_682:
	ds_read_b128 v[66:69], v212 offset:49152
	ds_read_b128 v[70:73], v212 offset:53248
	v_exp_f32_e32 v143, v138
	v_add_f32_e32 v138, v226, v177
	s_waitcnt lgkmcnt(1)
	v_mfma_f32_32x32x16_bf16 v[82:97], v[66:69], v[110:113], 0
	v_add_f32_e32 v138, v161, v138
	v_add_f32_e32 v138, v223, v138
	v_add_f32_e32 v138, v153, v138
	ds_read_b128 v[228:231], v216 offset:49152
	ds_read_b128 v[232:235], v216 offset:53248
	v_add_f32_e32 v138, v176, v138
	v_add_f32_e32 v138, v152, v138
	v_add_f32_e32 v138, v160, v138
	s_waitcnt lgkmcnt(2)
	v_mfma_f32_32x32x16_bf16 v[66:81], v[70:73], v[110:113], 0
	v_add_f32_e32 v138, v149, v138
	v_add_f32_e32 v138, v151, v138
	v_add_f32_e32 v138, v147, v138
	v_add_f32_e32 v138, v150, v138
	v_add_f32_e32 v138, v145, v138
	v_exp_f32_e32 v164, v139
	v_add_f32_e32 v138, v148, v138
	s_waitcnt lgkmcnt(1)
	v_mfma_f32_32x32x16_bf16 v[82:97], v[228:231], v[106:109], v[82:97]
	v_exp_f32_e32 v136, v136
	v_add_f32_e32 v138, v144, v138
	v_exp_f32_e32 v137, v137
	v_add_f32_e32 v138, v146, v138
	v_exp_f32_e32 v130, v130
	v_add_f32_e32 v138, v143, v138
	v_exp_f32_e32 v131, v131
	s_waitcnt lgkmcnt(0)
	v_mfma_f32_32x32x16_bf16 v[66:81], v[232:235], v[106:109], v[66:81]
	ds_read_b128 v[228:231], v217 offset:49152
	ds_read_b128 v[232:235], v217 offset:53248
	v_add_f32_e32 v138, v164, v138
	v_exp_f32_e32 v128, v128
	v_add_f32_e32 v138, v136, v138
	v_exp_f32_e32 v129, v129
	v_add_f32_e32 v138, v137, v138
	v_exp_f32_e32 v126, v126
	s_waitcnt lgkmcnt(1)
	v_mfma_f32_32x32x16_bf16 v[82:97], v[228:231], v[98:101], v[82:97]
	v_add_f32_e32 v138, v130, v138
	v_exp_f32_e32 v127, v127
	v_add_f32_e32 v138, v131, v138
	v_exp_f32_e32 v165, v140
	v_add_f32_e32 v138, v128, v138
	v_exp_f32_e32 v166, v141
	v_add_f32_e32 v138, v129, v138
	s_waitcnt lgkmcnt(0)
	v_mfma_f32_32x32x16_bf16 v[66:81], v[232:235], v[98:101], v[66:81]
	ds_read_b128 v[228:231], v218 offset:49152
	ds_read_b128 v[232:235], v218 offset:53248
	v_exp_f32_e32 v134, v134
	v_add_f32_e32 v138, v126, v138
	v_exp_f32_e32 v135, v135
	v_add_f32_e32 v138, v127, v138
	v_exp_f32_e32 v132, v132
	v_add_f32_e32 v138, v165, v138
	s_waitcnt lgkmcnt(1)
	v_mfma_f32_32x32x16_bf16 v[82:97], v[228:231], v[102:105], v[82:97]
	v_exp_f32_e32 v133, v133
	v_add_f32_e32 v138, v166, v138
	v_add_f32_e32 v138, v134, v138
	v_add_f32_e32 v138, v135, v138
	v_add_f32_e32 v138, v132, v138
	v_add_f32_e32 v220, v133, v138
	s_waitcnt lgkmcnt(0)
	v_mfma_f32_32x32x16_bf16 v[66:81], v[232:235], v[102:105], v[66:81]
	v_cvt_pk_bf16_f32 v138, v177, v226
	v_cvt_pk_bf16_f32 v139, v161, v223
	v_cvt_pk_bf16_f32 v140, v153, v176
	v_cvt_pk_bf16_f32 v141, v152, v160
	v_cvt_pk_bf16_f32 v222, v149, v151
	v_cvt_pk_bf16_f32 v223, v147, v150
	v_cvt_pk_bf16_f32 v224, v145, v148
	v_cvt_pk_bf16_f32 v225, v144, v146
	v_cvt_pk_bf16_f32 v144, v143, v164
	v_cvt_pk_bf16_f32 v145, v136, v137
	v_cvt_pk_bf16_f32 v146, v130, v131
	v_cvt_pk_bf16_f32 v147, v128, v129
	v_cvt_pk_bf16_f32 v148, v126, v127
	v_cvt_pk_bf16_f32 v149, v165, v166
	v_cvt_pk_bf16_f32 v150, v134, v135
	v_cvt_pk_bf16_f32 v151, v132, v133
	global_load_dwordx4 v[182:185], v[178:179], off offset:2048
	global_load_dwordx4 v[194:197], v[180:181], off offset:2048
	global_load_dwordx4 v[134:137], v[204:205], off offset:1024
	s_mov_b32 s4, 0xa0000
	s_mov_b32 s5, 0
	v_lshl_add_u64 v[178:179], v[178:179], 0, s[4:5]
	v_lshl_add_u64 v[180:181], v[180:181], 0, s[4:5]
	v_lshl_add_u64 v[204:205], v[204:205], 0, s[4:5]
	ds_read_b64_tr_b16 v[226:227], v211 offset:0
	ds_read_b64_tr_b16 v[228:229], v211 offset:0x800
	ds_read_b64_tr_b16 v[230:231], v211 offset:0x1000
	ds_read_b64_tr_b16 v[232:233], v211 offset:0x1800
	ds_read_b64_tr_b16 v[234:235], v211 offset:0x2000
	ds_read_b64_tr_b16 v[236:237], v211 offset:0x2800
	ds_read_b64_tr_b16 v[238:239], v211 offset:0x3000
	ds_read_b64_tr_b16 v[240:241], v211 offset:0x3800
	s_waitcnt lgkmcnt(4)
	s_nop 0
	v_mfma_f32_32x32x16_bf16 v[18:33], v[138:141], v[226:229], v[18:33]
	ds_read_b64_tr_b16 v[226:227], v211 offset:0x200
	ds_read_b64_tr_b16 v[228:229], v211 offset:0xa00
	v_mfma_f32_32x32x16_bf16 v[18:33], v[222:225], v[230:233], v[18:33]
	ds_read_b64_tr_b16 v[230:231], v211 offset:0x1200
	ds_read_b64_tr_b16 v[232:233], v211 offset:0x1a00
	s_waitcnt lgkmcnt(4)
	v_mfma_f32_32x32x16_bf16 v[18:33], v[144:147], v[234:237], v[18:33]
	ds_read_b64_tr_b16 v[234:235], v211 offset:0x2200
	ds_read_b64_tr_b16 v[236:237], v211 offset:0x2a00
	v_mfma_f32_32x32x16_bf16 v[18:33], v[148:151], v[238:241], v[18:33]
	ds_read_b64_tr_b16 v[238:239], v211 offset:0x3200
	ds_read_b64_tr_b16 v[240:241], v211 offset:0x3a00
	s_waitcnt lgkmcnt(4)
	v_mfma_f32_32x32x16_bf16 v[2:17], v[138:141], v[226:229], v[2:17]
	ds_read_b64_tr_b16 v[226:227], v211 offset:0x400
	ds_read_b64_tr_b16 v[228:229], v211 offset:0xc00
	v_mfma_f32_32x32x16_bf16 v[2:17], v[222:225], v[230:233], v[2:17]
	ds_read_b64_tr_b16 v[230:231], v211 offset:0x1400
	ds_read_b64_tr_b16 v[232:233], v211 offset:0x1c00
	s_waitcnt lgkmcnt(4)
	v_mfma_f32_32x32x16_bf16 v[2:17], v[144:147], v[234:237], v[2:17]
	ds_read_b64_tr_b16 v[234:235], v211 offset:0x2400
	ds_read_b64_tr_b16 v[236:237], v211 offset:0x2c00
	v_mfma_f32_32x32x16_bf16 v[2:17], v[148:151], v[238:241], v[2:17]
	ds_read_b64_tr_b16 v[238:239], v211 offset:0x3400
	ds_read_b64_tr_b16 v[240:241], v211 offset:0x3c00
	s_waitcnt lgkmcnt(4)
	v_mfma_f32_32x32x16_bf16 v[50:65], v[138:141], v[226:229], v[50:65]
	ds_read_b64_tr_b16 v[226:227], v211 offset:0x600
	ds_read_b64_tr_b16 v[228:229], v211 offset:0xe00
	v_mfma_f32_32x32x16_bf16 v[50:65], v[222:225], v[230:233], v[50:65]
	ds_read_b64_tr_b16 v[230:231], v211 offset:0x1600
	ds_read_b64_tr_b16 v[232:233], v211 offset:0x1e00
	s_waitcnt lgkmcnt(4)
; #define SBAR() __builtin_amdgcn_sched_barrier(0)
; __device__ __forceinline__ void partialSM(f32x16& p0, f32x16& p1, float& m_reg, float& mn, float& alpha, float C, float thrRaw) {
;   float pmax = p0[0];
; #pragma unroll
;   for (int r = 1; r < 16; ++r) pmax = fmaxf(pmax, p0[r]);
; #pragma unroll
;   for (int r = 0; r < 16; ++r) pmax = fmaxf(pmax, p1[r]);
;   { auto rr = __builtin_amdgcn_permlane32_swap(__float_as_uint(pmax), __float_as_uint(pmax), false, false);
;     pmax = fmaxf(__uint_as_float(rr[0]), __uint_as_float(rr[1])); }
;   if (__builtin_expect(__all(pmax - m_reg <= thrRaw), 1)) { mn = m_reg; alpha = 1.f; }
;   else { mn = fmaxf(m_reg, pmax); alpha = __builtin_amdgcn_exp2f((m_reg - mn) * C); m_reg = mn; }
; template <int D0> __device__ __forceinline__ void pv_one(f32x16& od, int vb, bf16x8 pa0, bf16x8 pa1, bf16x8 pa2, bf16x8 pa3) {
;   const s16x4 l0 = tr_read<v_rd_off(D0, 0, 0)>(vb), h0 = tr_read<v_rd_off(D0, 0, 1)>(vb), l1 = tr_read<v_rd_off(D0, 1, 0)>(vb), h1 = tr_read<v_rd_off(D0, 1, 1)>(vb);
;   const s16x4 l2 = tr_read<v_rd_off(D0, 2, 0)>(vb), h2 = tr_read<v_rd_off(D0, 2, 1)>(vb), l3 = tr_read<v_rd_off(D0, 3, 0)>(vb), h3 = tr_read<v_rd_off(D0, 3, 1)>(vb);
;   asm volatile("s_waitcnt lgkmcnt(0)" ::: "memory"); SBAR();
;     ...
;   od = __builtin_amdgcn_mfma_f32_32x32x16_bf16(pa0, PK(l0, h0), od, 0, 0, 0);
;   od = __builtin_amdgcn_mfma_f32_32x32x16_bf16(pa1, PK(l1, h1), od, 0, 0, 0);
;   od = __builtin_amdgcn_mfma_f32_32x32x16_bf16(pa2, PK(l2, h2), od, 0, 0, 0);
;   od = __builtin_amdgcn_mfma_f32_32x32x16_bf16(pa3, PK(l3, h3), od, 0, 0, 0);
;     ...
; }
; __device__ __forceinline__ void pv_d0(f32x16* o, int vb, bf16x8 pa0, bf16x8 pa1, bf16x8 pa2, bf16x8 pa3) {
;   pv_one<0>(o[0], vb, pa0, pa1, pa2, pa3); pv_one<1>(o[1], vb, pa0, pa1, pa2, pa3); pv_one<2>(o[2], vb, pa0, pa1, pa2, pa3); pv_one<3>(o[3], vb, pa0, pa1, pa2, pa3);
	v_mfma_f32_32x32x16_bf16 v[50:65], v[144:147], v[234:237], v[50:65]
	ds_read_b64_tr_b16 v[234:235], v211 offset:0x2600
	ds_read_b64_tr_b16 v[236:237], v211 offset:0x2e00
	v_mfma_f32_32x32x16_bf16 v[50:65], v[148:151], v[238:241], v[50:65]
	ds_read_b64_tr_b16 v[238:239], v211 offset:0x3600
	ds_read_b64_tr_b16 v[240:241], v211 offset:0x3e00
	s_waitcnt lgkmcnt(6)
	v_mfma_f32_32x32x16_bf16 v[34:49], v[138:141], v[226:229], v[34:49]
	v_max_f32_e32 v138, v83, v82
	v_max3_f32 v138, v138, v84, v85
	v_max3_f32 v138, v138, v86, v87
	v_max3_f32 v138, v138, v88, v89
	v_max3_f32 v138, v138, v90, v91
	v_max3_f32 v138, v138, v92, v93
	v_max3_f32 v138, v138, v94, v95
	s_waitcnt lgkmcnt(4)
	v_mfma_f32_32x32x16_bf16 v[34:49], v[222:225], v[230:233], v[34:49]
	v_max3_f32 v138, v138, v96, v97
	v_max3_f32 v138, v138, v66, v67
	v_max3_f32 v138, v138, v68, v69
	v_max3_f32 v138, v138, v70, v71
	v_max3_f32 v138, v138, v72, v73
	v_max3_f32 v138, v138, v74, v75
	v_max3_f32 v138, v138, v76, v77
	v_max3_f32 v138, v138, v78, v79
	s_waitcnt lgkmcnt(2)
	v_mfma_f32_32x32x16_bf16 v[34:49], v[144:147], v[234:237], v[34:49]
	v_max3_f32 v138, v138, v80, v81
	v_mov_b32_e32 v139, v138
	s_nop 1
	v_permlane32_swap_b32_e32 v138, v139
	v_max_f32_e32 v138, v139, v138
	v_sub_f32_e32 v139, v138, v142
	s_mov_b32 s2, 0x42800000
	v_cmp_ge_f32_e32 vcc, s2, v139
	v_max_f32_e32 v138, v142, v138
	s_waitcnt lgkmcnt(0)
	v_mfma_f32_32x32x16_bf16 v[34:49], v[148:151], v[238:241], v[34:49]
	v_sub_f32_e32 v139, v142, v138
	v_mul_f32_e32 v139, 0x3e38aa3b, v139
	v_exp_f32_e32 v139, v139
	s_cmp_eq_u64 vcc, exec
	s_cselect_b64 s[2:3], -1, 0
	s_waitcnt vmcnt(3)
	v_cndmask_b32_e64 v222, v139, 1.0, s[2:3]
	v_cmp_gt_f32_e32 vcc, 1.0, v222
	ds_write_b128 v213, v[122:125] offset:32768
	s_cbranch_vccz .LBB0_686
	s_and_saveexec_b64 s[4:5], s[0:1]
	ds_write_b32 v208, v222 offset:128
	s_or_b64 exec, exec, s[4:5]
	s_waitcnt lgkmcnt(0)
	v_add_u32_e32 v139, v207, v0
	ds_read_b128 v[144:147], v139 offset:128
	ds_read_b128 v[148:151], v139 offset:160
	ds_read_b128 v[224:227], v139 offset:192
	ds_read_b128 v[228:231], v139 offset:224
	s_waitcnt lgkmcnt(3)
	v_pk_mul_f32 v[2:3], v[144:145], v[2:3]
	v_pk_mul_f32 v[4:5], v[4:5], v[146:147]
	s_waitcnt lgkmcnt(2)
	v_pk_mul_f32 v[6:7], v[6:7], v[148:149]
	v_pk_mul_f32 v[8:9], v[8:9], v[150:151]
	s_waitcnt lgkmcnt(1)
	v_pk_mul_f32 v[10:11], v[10:11], v[224:225]
	v_pk_mul_f32 v[12:13], v[12:13], v[226:227]
	s_waitcnt lgkmcnt(0)
	v_pk_mul_f32 v[14:15], v[14:15], v[228:229]
	v_pk_mul_f32 v[30:31], v[30:31], v[228:229]
	v_pk_mul_f32 v[26:27], v[26:27], v[224:225]
	v_pk_mul_f32 v[22:23], v[22:23], v[148:149]
	v_pk_mul_f32 v[32:33], v[32:33], v[230:231]
	v_pk_mul_f32 v[28:29], v[28:29], v[226:227]
	v_pk_mul_f32 v[24:25], v[24:25], v[150:151]
	v_pk_mul_f32 v[20:21], v[20:21], v[146:147]
	v_pk_mul_f32 v[18:19], v[18:19], v[144:145]
	v_pk_mul_f32 v[16:17], v[16:17], v[230:231]
	v_pk_mul_f32 v[34:35], v[144:145], v[34:35]
	v_pk_mul_f32 v[36:37], v[36:37], v[146:147]
	v_pk_mul_f32 v[38:39], v[38:39], v[148:149]
	v_pk_mul_f32 v[40:41], v[40:41], v[150:151]
	v_pk_mul_f32 v[42:43], v[42:43], v[224:225]
	v_pk_mul_f32 v[44:45], v[44:45], v[226:227]
	v_pk_mul_f32 v[46:47], v[46:47], v[228:229]
	v_pk_mul_f32 v[62:63], v[62:63], v[228:229]
	v_pk_mul_f32 v[58:59], v[58:59], v[224:225]
	v_pk_mul_f32 v[54:55], v[54:55], v[148:149]
	v_pk_mul_f32 v[64:65], v[64:65], v[230:231]
	v_pk_mul_f32 v[60:61], v[60:61], v[226:227]
	v_pk_mul_f32 v[56:57], v[56:57], v[150:151]
	v_pk_mul_f32 v[52:53], v[52:53], v[146:147]
	v_pk_mul_f32 v[50:51], v[50:51], v[144:145]
	v_pk_mul_f32 v[48:49], v[48:49], v[230:231]
; #define SBAR() __builtin_amdgcn_sched_barrier(0)
; #define HOOK(P0, P1, j) do { if (NA) na_hook(P0, P1, krow0 + (j), q_row, q_col, win_r, win_c, rpb, inv_scale, hi); } while (0)
; __device__ __forceinline__ void partialSM(f32x16& p0, f32x16& p1, float& m_reg, float& mn, float& alpha, float C, float thrRaw) {
;     ...
;   float mnC = -mn * C;
; #pragma unroll
;   for (int r = 0; r < 16; ++r) p0[r] = fmaf(p0[r], C, mnC);
; #pragma unroll
;   for (int r = 0; r < 16; ++r) p1[r] = fmaf(p1[r], C, mnC);
; #pragma unroll
;   for (int r = 0; r < 16; ++r) p0[r] = __builtin_amdgcn_exp2f(p0[r]);
; }
; __device__ __forceinline__ void finishSM(f32x16& p0, f32x16& p1, float alpha, float& l_reg, bf16x8& pa0, bf16x8& pa1, bf16x8& pa2, bf16x8& pa3) {
; #pragma unroll
;   for (int r = 0; r < 16; ++r) p1[r] = __builtin_amdgcn_exp2f(p1[r]);
;   float ps = 0;
; #pragma unroll
;   for (int r = 0; r < 16; ++r) ps += p0[r];
; #pragma unroll
;   for (int r = 0; r < 16; ++r) ps += p1[r];
;   { auto rr = __builtin_amdgcn_permlane32_swap(__float_as_uint(ps), __float_as_uint(ps), false, false);
;     ps = __uint_as_float(rr[0]) + __uint_as_float(rr[1]); }
;   l_reg = l_reg * alpha + ps;
;     ...
;   PK4(p0, 0, pa0); PK4(p0, 8, pa1); PK4(p1, 0, pa2); PK4(p1, 8, pa3);
;     ...
; }
; template <int DK, bool QL>
; __device__ __forceinline__ void qkt(f32x16& p0, f32x16& p1, const bf16* Ks, const bf16x8* qr, const char* ql, int r32, int hi) {
;   p0 = f32x16{}; p1 = f32x16{};
; #pragma unroll
;   for (int d0 = 0; d0 < DK / 16; ++d0) { int cb = (d0 * 16 + hi * 8) * 2;
;     const bf16x8 qv = QL ? *reinterpret_cast<const bf16x8*>(ql + d0 * 1024) : qr[d0];
;     bf16x8 b0 = *reinterpret_cast<const bf16x8*>((const char*)Ks + kswz<DK>(r32, cb));
;     bf16x8 b1 = *reinterpret_cast<const bf16x8*>((const char*)Ks + kswz<DK>(32 + r32, cb));
;     p0 = __builtin_amdgcn_mfma_f32_32x32x16_bf16(b0, qv, p0, 0, 0, 0);
;     p1 = __builtin_amdgcn_mfma_f32_32x32x16_bf16(b1, qv, p1, 0, 0, 0); }
; }
; template <int DK, bool NA, bool QL, int SD> ...
;     ...
;     __syncthreads(); SWAIT(); SWRITE(0, SE);
;     RESC(alB); __syncthreads();
;     SBAR(); qkt<DK, QL>(pA0, pA1, K_lds, qr, ql, r32, hi); HOOK(pA0, pA1, j + 1);
;     finishSM(pB0, pB1, alB, l_reg, pa0, pa1, pa2, pa3); SBAR();
;     if (SD == 1 || j + 3 < NT) SLOAD(SE, (j + 1 + SD) * KVBLK); SBAR();
.LBB0_686:
	v_cndmask_b32_e64 v223, v138, v142, s[2:3]
	v_mul_f32_e32 v224, 0xbe38aa3b, v223
	s_mov_b32 s2, 0x3e38aa3b
	v_pk_fma_f32 v[82:83], v[82:83], s[2:3], v[224:225] op_sel_hi:[1,0,0]
	v_pk_fma_f32 v[84:85], v[84:85], s[2:3], v[224:225] op_sel_hi:[1,0,0]
	v_pk_fma_f32 v[86:87], v[86:87], s[2:3], v[224:225] op_sel_hi:[1,0,0]
	v_pk_fma_f32 v[88:89], v[88:89], s[2:3], v[224:225] op_sel_hi:[1,0,0]
	v_pk_fma_f32 v[90:91], v[90:91], s[2:3], v[224:225] op_sel_hi:[1,0,0]
	v_pk_fma_f32 v[92:93], v[92:93], s[2:3], v[224:225] op_sel_hi:[1,0,0]
	v_pk_fma_f32 v[94:95], v[94:95], s[2:3], v[224:225] op_sel_hi:[1,0,0]
	v_pk_fma_f32 v[96:97], v[96:97], s[2:3], v[224:225] op_sel_hi:[1,0,0]
	v_exp_f32_e32 v138, v82
	v_exp_f32_e32 v153, v83
	v_exp_f32_e32 v139, v84
	v_exp_f32_e32 v152, v85
	v_exp_f32_e32 v140, v86
	v_exp_f32_e32 v151, v87
	v_exp_f32_e32 v141, v88
	v_exp_f32_e32 v150, v89
	v_exp_f32_e32 v142, v90
	v_exp_f32_e32 v149, v91
	v_exp_f32_e32 v143, v92
	v_exp_f32_e32 v148, v93
	v_exp_f32_e32 v144, v94
	v_exp_f32_e32 v147, v95
	v_exp_f32_e32 v145, v96
	v_exp_f32_e32 v146, v97
	v_fmamk_f32 v233, v66, 0x3e38aa3b, v224
	v_fmamk_f32 v234, v67, 0x3e38aa3b, v224
	v_fmamk_f32 v235, v68, 0x3e38aa3b, v224
	v_fmamk_f32 v236, v69, 0x3e38aa3b, v224
	v_fmamk_f32 v237, v70, 0x3e38aa3b, v224
	v_fmamk_f32 v226, v71, 0x3e38aa3b, v224
	v_fmamk_f32 v227, v72, 0x3e38aa3b, v224
	v_fmamk_f32 v228, v73, 0x3e38aa3b, v224
	v_fmamk_f32 v229, v74, 0x3e38aa3b, v224
	v_fmamk_f32 v230, v75, 0x3e38aa3b, v224
	v_fmamk_f32 v231, v76, 0x3e38aa3b, v224
	v_fmamk_f32 v232, v77, 0x3e38aa3b, v224
	v_fmamk_f32 v225, v78, 0x3e38aa3b, v224
	v_fmamk_f32 v238, v79, 0x3e38aa3b, v224
	v_fmamk_f32 v239, v80, 0x3e38aa3b, v224
	v_fmac_f32_e32 v224, 0x3e38aa3b, v81
	s_waitcnt lgkmcnt(0)
	s_barrier
	ds_write_b128 v214, v[114:117]
	ds_write_b128 v215, v[118:121]
	ds_read_b128 v[66:69], v212 offset:32768
	ds_read_b128 v[70:73], v212 offset:36864
	v_exp_f32_e32 v164, v233
	v_exp_f32_e32 v233, v224
	v_add_f32_e32 v224, v153, v138
	s_waitcnt lgkmcnt(1)
	v_mfma_f32_32x32x16_bf16 v[82:97], v[66:69], v[110:113], 0
	v_add_f32_e32 v224, v139, v224
	v_add_f32_e32 v224, v152, v224
	v_add_f32_e32 v224, v140, v224
	ds_read_b128 v[240:243], v216 offset:32768
	ds_read_b128 v[244:247], v216 offset:36864
	v_add_f32_e32 v224, v151, v224
	v_add_f32_e32 v224, v141, v224
	v_add_f32_e32 v224, v150, v224
	s_waitcnt lgkmcnt(2)
	v_mfma_f32_32x32x16_bf16 v[66:81], v[70:73], v[110:113], 0
	v_add_f32_e32 v224, v142, v224
	v_add_f32_e32 v224, v149, v224
	v_add_f32_e32 v224, v143, v224
	v_add_f32_e32 v224, v148, v224
	v_add_f32_e32 v224, v144, v224
	v_exp_f32_e32 v165, v234
	v_add_f32_e32 v224, v147, v224
	s_waitcnt lgkmcnt(1)
	v_mfma_f32_32x32x16_bf16 v[82:97], v[240:243], v[106:109], v[82:97]
	v_exp_f32_e32 v166, v235
	v_add_f32_e32 v224, v145, v224
	v_exp_f32_e32 v167, v236
	v_add_f32_e32 v224, v146, v224
	v_exp_f32_e32 v172, v237
	v_add_f32_e32 v224, v164, v224
	v_exp_f32_e32 v173, v226
	s_waitcnt lgkmcnt(0)
	v_mfma_f32_32x32x16_bf16 v[66:81], v[244:247], v[106:109], v[66:81]
	ds_read_b128 v[240:243], v217 offset:32768
	ds_read_b128 v[244:247], v217 offset:36864
	v_add_f32_e32 v224, v165, v224
	v_exp_f32_e32 v174, v227
	v_add_f32_e32 v224, v166, v224
	v_exp_f32_e32 v175, v228
	v_add_f32_e32 v224, v167, v224
	v_exp_f32_e32 v226, v229
	s_waitcnt lgkmcnt(1)
	v_mfma_f32_32x32x16_bf16 v[82:97], v[240:243], v[98:101], v[82:97]
	v_add_f32_e32 v224, v172, v224
	v_exp_f32_e32 v227, v230
	v_add_f32_e32 v224, v173, v224
	v_exp_f32_e32 v228, v231
	v_add_f32_e32 v224, v174, v224
	v_exp_f32_e32 v229, v232
	v_add_f32_e32 v224, v175, v224
	s_waitcnt lgkmcnt(0)
	v_mfma_f32_32x32x16_bf16 v[66:81], v[244:247], v[98:101], v[66:81]
	ds_read_b128 v[240:243], v218 offset:32768
	ds_read_b128 v[244:247], v218 offset:36864
	v_exp_f32_e32 v230, v225
	v_add_f32_e32 v224, v226, v224
	v_exp_f32_e32 v231, v238
	v_add_f32_e32 v224, v227, v224
	v_exp_f32_e32 v232, v239
	v_add_f32_e32 v224, v228, v224
	s_waitcnt lgkmcnt(1)
	v_mfma_f32_32x32x16_bf16 v[82:97], v[240:243], v[102:105], v[82:97]
	v_add_f32_e32 v224, v229, v224
	v_add_f32_e32 v224, v230, v224
	v_add_f32_e32 v224, v231, v224
	v_add_f32_e32 v224, v232, v224
	v_add_f32_e32 v224, v233, v224
	v_cvt_pk_bf16_f32 v138, v138, v153
	s_waitcnt lgkmcnt(0)
	v_mfma_f32_32x32x16_bf16 v[66:81], v[244:247], v[102:105], v[66:81]
	v_cvt_pk_bf16_f32 v139, v139, v152
	v_cvt_pk_bf16_f32 v140, v140, v151
	v_cvt_pk_bf16_f32 v141, v141, v150
	v_cvt_pk_bf16_f32 v142, v142, v149
	v_cvt_pk_bf16_f32 v143, v143, v148
	v_cvt_pk_bf16_f32 v144, v144, v147
	v_cvt_pk_bf16_f32 v145, v145, v146
	v_cvt_pk_bf16_f32 v146, v164, v165
	v_cvt_pk_bf16_f32 v147, v166, v167
	v_cvt_pk_bf16_f32 v148, v172, v173
	v_cvt_pk_bf16_f32 v149, v174, v175
	v_cvt_pk_bf16_f32 v150, v226, v227
	v_cvt_pk_bf16_f32 v151, v228, v229
	v_cvt_pk_bf16_f32 v152, v230, v231
	v_cvt_pk_bf16_f32 v153, v232, v233
	s_cmp_gt_u32 s9, 60
	s_cselect_b64 s[4:5], -1, 0
	s_and_b64 vcc, exec, s[4:5]
	s_cbranch_vccnz .Lod_d1
	global_load_dwordx4 v[114:117], v[178:179], off offset:2048
	global_load_dwordx4 v[118:121], v[180:181], off offset:2048
	global_load_dwordx4 v[122:125], v[204:205], off offset:1024
	s_mov_b32 s6, 0xa0000
	s_mov_b32 s7, 0
	v_lshl_add_u64 v[178:179], v[178:179], 0, s[6:7]
	v_lshl_add_u64 v[180:181], v[180:181], 0, s[6:7]
	v_lshl_add_u64 v[204:205], v[204:205], 0, s[6:7]

; #define SBAR() __builtin_amdgcn_sched_barrier(0)
; #define SLOAD(i, k0) do { sr_[i].vs0 = *reinterpret_cast<const bf16x8*>(&Vh[(long)((k0) + sr) * LDP + sc]); sr_[i].vs1 = *reinterpret_cast<const bf16x8*>(&Vh[(long)((k0) + 32 + sr) * LDP + sc]); \
;     sr_[i].ks0 = *reinterpret_cast<const bf16x8*>(&Kh[(long)((k0) + ksr) * LDP + ksc]); if (DK == 128) sr_[i].ks1 = *reinterpret_cast<const bf16x8*>(&Kh[(long)((k0) + 32 + ksr) * LDP + ksc]); } while (0)
; #define SWAIT() do { if (SD == 1) asm volatile("s_waitcnt vmcnt(0)" ::: "memory"); else if (DK == 128) asm volatile("s_waitcnt vmcnt(4)" ::: "memory"); else asm volatile("s_waitcnt vmcnt(3)" ::: "memory"); } while (0)
; #define RESC(a) do { if (__any((a) < 1.f)) { if (hi == 0) al_l[r32] = (a); asm volatile("s_waitcnt lgkmcnt(0)" ::: "memory"); \
;     _Pragma("unroll") for (int d = 0; d < 4; ++d) _Pragma("unroll") for (int r = 0; r < 16; ++r) o[d][r] *= al_l[crow(r, hi)]; } } while (0)
; #define HOOK(P0, P1, j) do { if (NA) na_hook(P0, P1, krow0 + (j), q_row, q_col, win_r, win_c, rpb, inv_scale, hi); } while (0)
; __device__ __forceinline__ void partialSM(f32x16& p0, f32x16& p1, float& m_reg, float& mn, float& alpha, float C, float thrRaw) {
;     ...
;   float mnC = -mn * C;
; #pragma unroll
;   for (int r = 0; r < 16; ++r) p0[r] = fmaf(p0[r], C, mnC);
; #pragma unroll
;   for (int r = 0; r < 16; ++r) p1[r] = fmaf(p1[r], C, mnC);
; #pragma unroll
;   for (int r = 0; r < 16; ++r) p0[r] = __builtin_amdgcn_exp2f(p0[r]);
; template <int DK, bool NA, bool QL, int SD> ...
;     ...
;     __syncthreads(); SWAIT(); SWRITE(0, SE);
;     RESC(alB); __syncthreads();
;     SBAR(); qkt<DK, QL>(pA0, pA1, K_lds, qr, ql, r32, hi); HOOK(pA0, pA1, j + 1);
;     finishSM(pB0, pB1, alB, l_reg, pa0, pa1, pa2, pa3); SBAR();
;     if (SD == 1 || j + 3 < NT) SLOAD(SE, (j + 1 + SD) * KVBLK); SBAR();
;     pv_d0(o, vb0 + (int)SHM_V, pa0, pa1, pa2, pa3); partialSM(pA0, pA1, m_reg, mnA, alA, C, thrRaw);
;     __syncthreads(); SWAIT(); SWRITE(1, SO);
;     RESC(alA); __syncthreads();
;   }
.LBB0_692:
	v_cndmask_b32_e64 v142, v138, v223, s[2:3]
	v_mul_f32_e32 v132, 0xbe38aa3b, v142
	s_mov_b32 s2, 0x3e38aa3b
	v_pk_fma_f32 v[82:83], v[82:83], s[2:3], v[132:133] op_sel_hi:[1,0,0]
	v_pk_fma_f32 v[84:85], v[84:85], s[2:3], v[132:133] op_sel_hi:[1,0,0]
	v_pk_fma_f32 v[86:87], v[86:87], s[2:3], v[132:133] op_sel_hi:[1,0,0]
	v_pk_fma_f32 v[88:89], v[88:89], s[2:3], v[132:133] op_sel_hi:[1,0,0]
	v_pk_fma_f32 v[90:91], v[90:91], s[2:3], v[132:133] op_sel_hi:[1,0,0]
	v_pk_fma_f32 v[92:93], v[92:93], s[2:3], v[132:133] op_sel_hi:[1,0,0]
	v_pk_fma_f32 v[94:95], v[94:95], s[2:3], v[132:133] op_sel_hi:[1,0,0]
	v_pk_fma_f32 v[96:97], v[96:97], s[2:3], v[132:133] op_sel_hi:[1,0,0]
	s_mov_b32 s2, 0x3e38aa3b
	v_exp_f32_e32 v177, v82
	v_exp_f32_e32 v226, v83
	v_exp_f32_e32 v161, v84
	v_exp_f32_e32 v223, v85
	v_exp_f32_e32 v153, v86
	v_exp_f32_e32 v176, v87
	v_exp_f32_e32 v152, v88
	v_exp_f32_e32 v160, v89
	v_exp_f32_e32 v149, v90
	v_exp_f32_e32 v151, v91
	v_exp_f32_e32 v147, v92
	v_exp_f32_e32 v150, v93
	v_exp_f32_e32 v145, v94
	v_exp_f32_e32 v148, v95
	v_exp_f32_e32 v144, v96
	v_exp_f32_e32 v146, v97
	v_pk_fma_f32 v[138:139], v[66:67], s[2:3], v[132:133] op_sel_hi:[1,0,0]
	v_pk_fma_f32 v[136:137], v[68:69], s[2:3], v[132:133] op_sel_hi:[1,0,0]
	v_pk_fma_f32 v[130:131], v[70:71], s[2:3], v[132:133] op_sel_hi:[1,0,0]
	v_pk_fma_f32 v[128:129], v[72:73], s[2:3], v[132:133] op_sel_hi:[1,0,0]
	v_pk_fma_f32 v[126:127], v[74:75], s[2:3], v[132:133] op_sel_hi:[1,0,0]
	v_pk_fma_f32 v[140:141], v[76:77], s[2:3], v[132:133] op_sel_hi:[1,0,0]
	v_pk_fma_f32 v[134:135], v[78:79], s[2:3], v[132:133] op_sel_hi:[1,0,0]
	v_pk_fma_f32 v[132:133], v[80:81], s[2:3], v[132:133] op_sel_hi:[1,0,0]
	v_fma_f32 v66, v219, v209, v220
	v_fma_f32 v209, v66, v222, v224
	s_add_i32 s9, s9, 2
	s_and_b64 vcc, exec, s[4:5]
	s_waitcnt lgkmcnt(0)
	s_barrier
	s_cbranch_vccnz .LBB0_694
	v_mov_b32_e32 v219, v143
	ds_write_b128 v214, v[182:185] offset:16384
	ds_write_b128 v215, v[194:197] offset:16384
	s_branch .LBB0_682

; #define SBAR() __builtin_amdgcn_sched_barrier(0)
; __device__ __forceinline__ void finishSM(f32x16& p0, f32x16& p1, float alpha, float& l_reg, bf16x8& pa0, bf16x8& pa1, bf16x8& pa2, bf16x8& pa3) {
; #pragma unroll
;   for (int r = 0; r < 16; ++r) p1[r] = __builtin_amdgcn_exp2f(p1[r]);
;   float ps = 0;
; #pragma unroll
;   for (int r = 0; r < 16; ++r) ps += p0[r];
; #pragma unroll
;   for (int r = 0; r < 16; ++r) ps += p1[r];
;   { auto rr = __builtin_amdgcn_permlane32_swap(__float_as_uint(ps), __float_as_uint(ps), false, false);
;     ps = __uint_as_float(rr[0]) + __uint_as_float(rr[1]); }
;   l_reg = l_reg * alpha + ps;
;     ...
;   PK4(p0, 0, pa0); PK4(p0, 8, pa1); PK4(p1, 0, pa2); PK4(p1, 8, pa3);
;     ...
; }
; template <int DK, bool QL>
; __device__ __forceinline__ void qkt(f32x16& p0, f32x16& p1, const bf16* Ks, const bf16x8* qr, const char* ql, int r32, int hi) {
;   p0 = f32x16{}; p1 = f32x16{};
; #pragma unroll
;   for (int d0 = 0; d0 < DK / 16; ++d0) { int cb = (d0 * 16 + hi * 8) * 2;
;     const bf16x8 qv = QL ? *reinterpret_cast<const bf16x8*>(ql + d0 * 1024) : qr[d0];
;     bf16x8 b0 = *reinterpret_cast<const bf16x8*>((const char*)Ks + kswz<DK>(r32, cb));
;     bf16x8 b1 = *reinterpret_cast<const bf16x8*>((const char*)Ks + kswz<DK>(32 + r32, cb));
;     p0 = __builtin_amdgcn_mfma_f32_32x32x16_bf16(b0, qv, p0, 0, 0, 0);
;     p1 = __builtin_amdgcn_mfma_f32_32x32x16_bf16(b1, qv, p1, 0, 0, 0); }
; }
; template <int D0> __device__ __forceinline__ void pv_one(f32x16& od, int vb, bf16x8 pa0, bf16x8 pa1, bf16x8 pa2, bf16x8 pa3) {
;   const s16x4 l0 = tr_read<v_rd_off(D0, 0, 0)>(vb), h0 = tr_read<v_rd_off(D0, 0, 1)>(vb), l1 = tr_read<v_rd_off(D0, 1, 0)>(vb), h1 = tr_read<v_rd_off(D0, 1, 1)>(vb);
;   const s16x4 l2 = tr_read<v_rd_off(D0, 2, 0)>(vb), h2 = tr_read<v_rd_off(D0, 2, 1)>(vb), l3 = tr_read<v_rd_off(D0, 3, 0)>(vb), h3 = tr_read<v_rd_off(D0, 3, 1)>(vb);
;   asm volatile("s_waitcnt lgkmcnt(0)" ::: "memory"); SBAR();
;     ...
;   od = __builtin_amdgcn_mfma_f32_32x32x16_bf16(pa0, PK(l0, h0), od, 0, 0, 0);
;   od = __builtin_amdgcn_mfma_f32_32x32x16_bf16(pa1, PK(l1, h1), od, 0, 0, 0);
;   od = __builtin_amdgcn_mfma_f32_32x32x16_bf16(pa2, PK(l2, h2), od, 0, 0, 0);
;   od = __builtin_amdgcn_mfma_f32_32x32x16_bf16(pa3, PK(l3, h3), od, 0, 0, 0);
;     ...
; }
; __device__ __forceinline__ void pv_d0(f32x16* o, int vb, bf16x8 pa0, bf16x8 pa1, bf16x8 pa2, bf16x8 pa3) {
.LBB0_701:
	ds_read_b128 v[66:69], v215 offset:49152
	ds_read_b128 v[70:73], v215 offset:53248
	v_exp_f32_e32 v143, v138
	v_add_f32_e32 v138, v226, v177
	s_waitcnt lgkmcnt(1)
	v_mfma_f32_32x32x16_bf16 v[82:97], v[66:69], v[110:113], 0
	v_add_f32_e32 v138, v161, v138
	v_add_f32_e32 v138, v223, v138
	v_add_f32_e32 v138, v153, v138
	ds_read_b128 v[228:231], v216 offset:49152
	ds_read_b128 v[232:235], v216 offset:53248
	v_add_f32_e32 v138, v176, v138
	v_add_f32_e32 v138, v152, v138
	v_add_f32_e32 v138, v160, v138
	s_waitcnt lgkmcnt(2)
	v_mfma_f32_32x32x16_bf16 v[66:81], v[70:73], v[110:113], 0
	v_add_f32_e32 v138, v149, v138
	v_add_f32_e32 v138, v151, v138
	v_add_f32_e32 v138, v147, v138
	v_add_f32_e32 v138, v150, v138
	v_add_f32_e32 v138, v145, v138
	v_exp_f32_e32 v164, v139
	v_add_f32_e32 v138, v148, v138
	s_waitcnt lgkmcnt(1)
	v_mfma_f32_32x32x16_bf16 v[82:97], v[228:231], v[106:109], v[82:97]
	v_exp_f32_e32 v136, v136
	v_add_f32_e32 v138, v144, v138
	v_exp_f32_e32 v137, v137
	v_add_f32_e32 v138, v146, v138
	v_exp_f32_e32 v130, v130
	v_add_f32_e32 v138, v143, v138
	v_exp_f32_e32 v131, v131
	s_waitcnt lgkmcnt(0)
	v_mfma_f32_32x32x16_bf16 v[66:81], v[232:235], v[106:109], v[66:81]
	ds_read_b128 v[228:231], v217 offset:49152
	ds_read_b128 v[232:235], v217 offset:53248
	v_add_f32_e32 v138, v164, v138
	v_exp_f32_e32 v128, v128
	v_add_f32_e32 v138, v136, v138
	v_exp_f32_e32 v129, v129
	v_add_f32_e32 v138, v137, v138
	v_exp_f32_e32 v126, v126
	s_waitcnt lgkmcnt(1)
	v_mfma_f32_32x32x16_bf16 v[82:97], v[228:231], v[102:105], v[82:97]
	v_add_f32_e32 v138, v130, v138
	v_exp_f32_e32 v127, v127
	v_add_f32_e32 v138, v131, v138
	v_exp_f32_e32 v165, v140
	v_add_f32_e32 v138, v128, v138
	v_exp_f32_e32 v166, v141
	v_add_f32_e32 v138, v129, v138
	s_waitcnt lgkmcnt(0)
	v_mfma_f32_32x32x16_bf16 v[66:81], v[232:235], v[102:105], v[66:81]
	ds_read_b128 v[228:231], v218 offset:49152
	ds_read_b128 v[232:235], v218 offset:53248
	v_exp_f32_e32 v134, v134
	v_add_f32_e32 v138, v126, v138
	v_exp_f32_e32 v135, v135
	v_add_f32_e32 v138, v127, v138
	v_exp_f32_e32 v132, v132
	v_add_f32_e32 v138, v165, v138
	s_waitcnt lgkmcnt(1)
	v_mfma_f32_32x32x16_bf16 v[82:97], v[228:231], v[98:101], v[82:97]
	v_exp_f32_e32 v133, v133
	v_add_f32_e32 v138, v166, v138
	v_add_f32_e32 v138, v134, v138
	v_add_f32_e32 v138, v135, v138
	v_add_f32_e32 v138, v132, v138
	v_add_f32_e32 v220, v133, v138
	s_waitcnt lgkmcnt(0)
	v_mfma_f32_32x32x16_bf16 v[66:81], v[232:235], v[98:101], v[66:81]
	v_cvt_pk_bf16_f32 v138, v177, v226
	v_cvt_pk_bf16_f32 v139, v161, v223
	v_cvt_pk_bf16_f32 v140, v153, v176
	v_cvt_pk_bf16_f32 v141, v152, v160
	v_cvt_pk_bf16_f32 v222, v149, v151
	v_cvt_pk_bf16_f32 v223, v147, v150
	v_cvt_pk_bf16_f32 v224, v145, v148
	v_cvt_pk_bf16_f32 v225, v144, v146
	v_cvt_pk_bf16_f32 v144, v143, v164
	v_cvt_pk_bf16_f32 v145, v136, v137
	v_cvt_pk_bf16_f32 v146, v130, v131
	v_cvt_pk_bf16_f32 v147, v128, v129
	v_cvt_pk_bf16_f32 v148, v126, v127
	v_cvt_pk_bf16_f32 v149, v165, v166
	v_cvt_pk_bf16_f32 v150, v134, v135
	v_cvt_pk_bf16_f32 v151, v132, v133
	global_load_dwordx4 v[182:185], v[178:179], off offset:2048
	global_load_dwordx4 v[194:197], v[180:181], off offset:2048
	global_load_dwordx4 v[134:137], v[204:205], off offset:1152
	s_mov_b32 s4, 0xa0000
	s_mov_b32 s5, 0
	v_lshl_add_u64 v[178:179], v[178:179], 0, s[4:5]
	v_lshl_add_u64 v[180:181], v[180:181], 0, s[4:5]
	v_lshl_add_u64 v[204:205], v[204:205], 0, s[4:5]
	ds_read_b64_tr_b16 v[226:227], v211 offset:0
	ds_read_b64_tr_b16 v[228:229], v211 offset:0x800
	ds_read_b64_tr_b16 v[230:231], v211 offset:0x1000
	ds_read_b64_tr_b16 v[232:233], v211 offset:0x1800
	ds_read_b64_tr_b16 v[234:235], v211 offset:0x2000
	ds_read_b64_tr_b16 v[236:237], v211 offset:0x2800
	ds_read_b64_tr_b16 v[238:239], v211 offset:0x3000
	ds_read_b64_tr_b16 v[240:241], v211 offset:0x3800
	s_waitcnt lgkmcnt(4)
	s_nop 0
	v_mfma_f32_32x32x16_bf16 v[2:17], v[138:141], v[226:229], v[2:17]
	ds_read_b64_tr_b16 v[226:227], v211 offset:0x200
	ds_read_b64_tr_b16 v[228:229], v211 offset:0xa00
	v_mfma_f32_32x32x16_bf16 v[2:17], v[222:225], v[230:233], v[2:17]
	ds_read_b64_tr_b16 v[230:231], v211 offset:0x1200
	ds_read_b64_tr_b16 v[232:233], v211 offset:0x1a00
	s_waitcnt lgkmcnt(4)
	v_mfma_f32_32x32x16_bf16 v[2:17], v[144:147], v[234:237], v[2:17]
	ds_read_b64_tr_b16 v[234:235], v211 offset:0x2200
	ds_read_b64_tr_b16 v[236:237], v211 offset:0x2a00
	v_mfma_f32_32x32x16_bf16 v[2:17], v[148:151], v[238:241], v[2:17]
	ds_read_b64_tr_b16 v[238:239], v211 offset:0x3200
	ds_read_b64_tr_b16 v[240:241], v211 offset:0x3a00
	s_waitcnt lgkmcnt(4)
	v_mfma_f32_32x32x16_bf16 v[50:65], v[138:141], v[226:229], v[50:65]
	ds_read_b64_tr_b16 v[226:227], v211 offset:0x400
	ds_read_b64_tr_b16 v[228:229], v211 offset:0xc00
	v_mfma_f32_32x32x16_bf16 v[50:65], v[222:225], v[230:233], v[50:65]
	ds_read_b64_tr_b16 v[230:231], v211 offset:0x1400
	ds_read_b64_tr_b16 v[232:233], v211 offset:0x1c00
	s_waitcnt lgkmcnt(4)
	v_mfma_f32_32x32x16_bf16 v[50:65], v[144:147], v[234:237], v[50:65]
	ds_read_b64_tr_b16 v[234:235], v211 offset:0x2400
	ds_read_b64_tr_b16 v[236:237], v211 offset:0x2c00
	v_mfma_f32_32x32x16_bf16 v[50:65], v[148:151], v[238:241], v[50:65]
	ds_read_b64_tr_b16 v[238:239], v211 offset:0x3400
	ds_read_b64_tr_b16 v[240:241], v211 offset:0x3c00
	s_waitcnt lgkmcnt(4)
	v_mfma_f32_32x32x16_bf16 v[34:49], v[138:141], v[226:229], v[34:49]
	ds_read_b64_tr_b16 v[226:227], v211 offset:0x600
	ds_read_b64_tr_b16 v[228:229], v211 offset:0xe00
	v_mfma_f32_32x32x16_bf16 v[34:49], v[222:225], v[230:233], v[34:49]
	ds_read_b64_tr_b16 v[230:231], v211 offset:0x1600
	ds_read_b64_tr_b16 v[232:233], v211 offset:0x1e00
	s_waitcnt lgkmcnt(4)
; #define SBAR() __builtin_amdgcn_sched_barrier(0)
; __device__ __forceinline__ void partialSM(f32x16& p0, f32x16& p1, float& m_reg, float& mn, float& alpha, float C, float thrRaw) {
;   float pmax = p0[0];
; #pragma unroll
;   for (int r = 1; r < 16; ++r) pmax = fmaxf(pmax, p0[r]);
; #pragma unroll
;   for (int r = 0; r < 16; ++r) pmax = fmaxf(pmax, p1[r]);
;   { auto rr = __builtin_amdgcn_permlane32_swap(__float_as_uint(pmax), __float_as_uint(pmax), false, false);
;     pmax = fmaxf(__uint_as_float(rr[0]), __uint_as_float(rr[1])); }
;   if (__builtin_expect(__all(pmax - m_reg <= thrRaw), 1)) { mn = m_reg; alpha = 1.f; }
;   else { mn = fmaxf(m_reg, pmax); alpha = __builtin_amdgcn_exp2f((m_reg - mn) * C); m_reg = mn; }
; template <int D0> __device__ __forceinline__ void pv_one(f32x16& od, int vb, bf16x8 pa0, bf16x8 pa1, bf16x8 pa2, bf16x8 pa3) {
;   const s16x4 l0 = tr_read<v_rd_off(D0, 0, 0)>(vb), h0 = tr_read<v_rd_off(D0, 0, 1)>(vb), l1 = tr_read<v_rd_off(D0, 1, 0)>(vb), h1 = tr_read<v_rd_off(D0, 1, 1)>(vb);
;   const s16x4 l2 = tr_read<v_rd_off(D0, 2, 0)>(vb), h2 = tr_read<v_rd_off(D0, 2, 1)>(vb), l3 = tr_read<v_rd_off(D0, 3, 0)>(vb), h3 = tr_read<v_rd_off(D0, 3, 1)>(vb);
;   asm volatile("s_waitcnt lgkmcnt(0)" ::: "memory"); SBAR();
;     ...
;   od = __builtin_amdgcn_mfma_f32_32x32x16_bf16(pa0, PK(l0, h0), od, 0, 0, 0);
;   od = __builtin_amdgcn_mfma_f32_32x32x16_bf16(pa1, PK(l1, h1), od, 0, 0, 0);
;   od = __builtin_amdgcn_mfma_f32_32x32x16_bf16(pa2, PK(l2, h2), od, 0, 0, 0);
;   od = __builtin_amdgcn_mfma_f32_32x32x16_bf16(pa3, PK(l3, h3), od, 0, 0, 0);
;     ...
; }
; __device__ __forceinline__ void pv_d0(f32x16* o, int vb, bf16x8 pa0, bf16x8 pa1, bf16x8 pa2, bf16x8 pa3) {
;   pv_one<0>(o[0], vb, pa0, pa1, pa2, pa3); pv_one<1>(o[1], vb, pa0, pa1, pa2, pa3); pv_one<2>(o[2], vb, pa0, pa1, pa2, pa3); pv_one<3>(o[3], vb, pa0, pa1, pa2, pa3);
	v_mfma_f32_32x32x16_bf16 v[34:49], v[144:147], v[234:237], v[34:49]
	ds_read_b64_tr_b16 v[234:235], v211 offset:0x2600
	ds_read_b64_tr_b16 v[236:237], v211 offset:0x2e00
	v_mfma_f32_32x32x16_bf16 v[34:49], v[148:151], v[238:241], v[34:49]
	ds_read_b64_tr_b16 v[238:239], v211 offset:0x3600
	ds_read_b64_tr_b16 v[240:241], v211 offset:0x3e00
	s_waitcnt lgkmcnt(6)
	v_mfma_f32_32x32x16_bf16 v[18:33], v[138:141], v[226:229], v[18:33]
	v_max_f32_e32 v138, v83, v82
	v_max3_f32 v138, v138, v84, v85
	v_max3_f32 v138, v138, v86, v87
	v_max3_f32 v138, v138, v88, v89
	v_max3_f32 v138, v138, v90, v91
	v_max3_f32 v138, v138, v92, v93
	v_max3_f32 v138, v138, v94, v95
	s_waitcnt lgkmcnt(4)
	v_mfma_f32_32x32x16_bf16 v[18:33], v[222:225], v[230:233], v[18:33]
	v_max3_f32 v138, v138, v96, v97
	v_max3_f32 v138, v138, v66, v67
	v_max3_f32 v138, v138, v68, v69
	v_max3_f32 v138, v138, v70, v71
	v_max3_f32 v138, v138, v72, v73
	v_max3_f32 v138, v138, v74, v75
	v_max3_f32 v138, v138, v76, v77
	v_max3_f32 v138, v138, v78, v79
	s_waitcnt lgkmcnt(2)
	v_mfma_f32_32x32x16_bf16 v[18:33], v[144:147], v[234:237], v[18:33]
	v_max3_f32 v138, v138, v80, v81
	v_mov_b32_e32 v139, v138
	s_nop 1
	v_permlane32_swap_b32_e32 v138, v139
	v_max_f32_e32 v138, v139, v138
	v_sub_f32_e32 v139, v138, v142
	s_mov_b32 s2, 0x42800000
	v_cmp_ge_f32_e32 vcc, s2, v139
	v_max_f32_e32 v138, v142, v138
	s_waitcnt lgkmcnt(0)
	v_mfma_f32_32x32x16_bf16 v[18:33], v[148:151], v[238:241], v[18:33]
	v_sub_f32_e32 v139, v142, v138
	v_mul_f32_e32 v139, 0x3e38aa3b, v139
	v_exp_f32_e32 v139, v139
	s_cmp_eq_u64 vcc, exec
	s_cselect_b64 s[2:3], -1, 0
	s_waitcnt vmcnt(3)
	v_cndmask_b32_e64 v222, v139, 1.0, s[2:3]
	v_cmp_gt_f32_e32 vcc, 1.0, v222
	ds_write_b128 v214, v[122:125] offset:32768
	s_cbranch_vccz .LBB0_705
	s_and_saveexec_b64 s[4:5], s[0:1]
	ds_write_b32 v208, v222 offset:128
	s_or_b64 exec, exec, s[4:5]
	s_waitcnt lgkmcnt(0)
	v_add_u32_e32 v139, v207, v0
	ds_read_b128 v[144:147], v139 offset:224
	ds_read_b128 v[148:151], v139 offset:192
	ds_read_b128 v[224:227], v139 offset:160
	ds_read_b128 v[228:231], v139 offset:128
	s_waitcnt lgkmcnt(3)
	v_pk_mul_f32 v[14:15], v[14:15], v[144:145]
	s_waitcnt lgkmcnt(2)
	v_pk_mul_f32 v[10:11], v[10:11], v[148:149]
	s_waitcnt lgkmcnt(1)
	v_pk_mul_f32 v[6:7], v[6:7], v[224:225]
	v_pk_mul_f32 v[16:17], v[16:17], v[146:147]
	v_pk_mul_f32 v[12:13], v[12:13], v[150:151]
	v_pk_mul_f32 v[8:9], v[8:9], v[226:227]
	s_waitcnt lgkmcnt(0)
	v_pk_mul_f32 v[4:5], v[4:5], v[230:231]
	v_pk_mul_f32 v[2:3], v[2:3], v[228:229]
	v_pk_mul_f32 v[62:63], v[144:145], v[62:63]
	v_pk_mul_f32 v[58:59], v[148:149], v[58:59]
	v_pk_mul_f32 v[54:55], v[224:225], v[54:55]
	v_pk_mul_f32 v[64:65], v[146:147], v[64:65]
	v_pk_mul_f32 v[60:61], v[150:151], v[60:61]
	v_pk_mul_f32 v[56:57], v[226:227], v[56:57]
	v_pk_mul_f32 v[52:53], v[230:231], v[52:53]
	v_pk_mul_f32 v[50:51], v[228:229], v[50:51]
	v_pk_mul_f32 v[46:47], v[144:145], v[46:47]
	v_pk_mul_f32 v[42:43], v[148:149], v[42:43]
	v_pk_mul_f32 v[38:39], v[224:225], v[38:39]
	v_pk_mul_f32 v[48:49], v[146:147], v[48:49]
	v_pk_mul_f32 v[44:45], v[150:151], v[44:45]
	v_pk_mul_f32 v[40:41], v[226:227], v[40:41]
	v_pk_mul_f32 v[36:37], v[230:231], v[36:37]
	v_pk_mul_f32 v[34:35], v[228:229], v[34:35]
	v_pk_mul_f32 v[30:31], v[144:145], v[30:31]
	v_pk_mul_f32 v[26:27], v[148:149], v[26:27]
	v_pk_mul_f32 v[22:23], v[224:225], v[22:23]
	v_pk_mul_f32 v[32:33], v[146:147], v[32:33]
	v_pk_mul_f32 v[28:29], v[150:151], v[28:29]
	v_pk_mul_f32 v[24:25], v[226:227], v[24:25]
	v_pk_mul_f32 v[20:21], v[230:231], v[20:21]
	v_pk_mul_f32 v[18:19], v[228:229], v[18:19]
; #define SBAR() __builtin_amdgcn_sched_barrier(0)
; #define HOOK(P0, P1, j) do { if (NA) na_hook(P0, P1, krow0 + (j), q_row, q_col, win_r, win_c, rpb, inv_scale, hi); } while (0)
; __device__ __forceinline__ void partialSM(f32x16& p0, f32x16& p1, float& m_reg, float& mn, float& alpha, float C, float thrRaw) {
;     ...
;   float mnC = -mn * C;
; #pragma unroll
;   for (int r = 0; r < 16; ++r) p0[r] = fmaf(p0[r], C, mnC);
; #pragma unroll
;   for (int r = 0; r < 16; ++r) p1[r] = fmaf(p1[r], C, mnC);
; #pragma unroll
;   for (int r = 0; r < 16; ++r) p0[r] = __builtin_amdgcn_exp2f(p0[r]);
; }
; __device__ __forceinline__ void finishSM(f32x16& p0, f32x16& p1, float alpha, float& l_reg, bf16x8& pa0, bf16x8& pa1, bf16x8& pa2, bf16x8& pa3) {
; #pragma unroll
;   for (int r = 0; r < 16; ++r) p1[r] = __builtin_amdgcn_exp2f(p1[r]);
;   float ps = 0;
; #pragma unroll
;   for (int r = 0; r < 16; ++r) ps += p0[r];
; #pragma unroll
;   for (int r = 0; r < 16; ++r) ps += p1[r];
;   { auto rr = __builtin_amdgcn_permlane32_swap(__float_as_uint(ps), __float_as_uint(ps), false, false);
;     ps = __uint_as_float(rr[0]) + __uint_as_float(rr[1]); }
;   l_reg = l_reg * alpha + ps;
;     ...
;   PK4(p0, 0, pa0); PK4(p0, 8, pa1); PK4(p1, 0, pa2); PK4(p1, 8, pa3);
;     ...
; }
; template <int DK, bool QL>
; __device__ __forceinline__ void qkt(f32x16& p0, f32x16& p1, const bf16* Ks, const bf16x8* qr, const char* ql, int r32, int hi) {
;   p0 = f32x16{}; p1 = f32x16{};
; #pragma unroll
;   for (int d0 = 0; d0 < DK / 16; ++d0) { int cb = (d0 * 16 + hi * 8) * 2;
;     const bf16x8 qv = QL ? *reinterpret_cast<const bf16x8*>(ql + d0 * 1024) : qr[d0];
;     bf16x8 b0 = *reinterpret_cast<const bf16x8*>((const char*)Ks + kswz<DK>(r32, cb));
;     bf16x8 b1 = *reinterpret_cast<const bf16x8*>((const char*)Ks + kswz<DK>(32 + r32, cb));
;     p0 = __builtin_amdgcn_mfma_f32_32x32x16_bf16(b0, qv, p0, 0, 0, 0);
;     p1 = __builtin_amdgcn_mfma_f32_32x32x16_bf16(b1, qv, p1, 0, 0, 0); }
; }
; template <int DK, bool NA, bool QL, int SD> ...
;     ...
;     __syncthreads(); SWAIT(); SWRITE(0, SE);
;     RESC(alB); __syncthreads();
;     SBAR(); qkt<DK, QL>(pA0, pA1, K_lds, qr, ql, r32, hi); HOOK(pA0, pA1, j + 1);
;     finishSM(pB0, pB1, alB, l_reg, pa0, pa1, pa2, pa3); SBAR();
;     if (SD == 1 || j + 3 < NT) SLOAD(SE, (j + 1 + SD) * KVBLK); SBAR();
.LBB0_705:
	v_cndmask_b32_e64 v223, v138, v142, s[2:3]
	v_mul_f32_e32 v224, 0xbe38aa3b, v223
	s_mov_b32 s2, 0x3e38aa3b
	v_pk_fma_f32 v[82:83], v[82:83], s[2:3], v[224:225] op_sel_hi:[1,0,0]
	v_pk_fma_f32 v[84:85], v[84:85], s[2:3], v[224:225] op_sel_hi:[1,0,0]
	v_pk_fma_f32 v[86:87], v[86:87], s[2:3], v[224:225] op_sel_hi:[1,0,0]
	v_pk_fma_f32 v[88:89], v[88:89], s[2:3], v[224:225] op_sel_hi:[1,0,0]
	v_pk_fma_f32 v[90:91], v[90:91], s[2:3], v[224:225] op_sel_hi:[1,0,0]
	v_pk_fma_f32 v[92:93], v[92:93], s[2:3], v[224:225] op_sel_hi:[1,0,0]
	v_pk_fma_f32 v[94:95], v[94:95], s[2:3], v[224:225] op_sel_hi:[1,0,0]
	v_pk_fma_f32 v[96:97], v[96:97], s[2:3], v[224:225] op_sel_hi:[1,0,0]
	v_exp_f32_e32 v138, v82
	v_exp_f32_e32 v153, v83
	v_exp_f32_e32 v139, v84
	v_exp_f32_e32 v152, v85
	v_exp_f32_e32 v140, v86
	v_exp_f32_e32 v151, v87
	v_exp_f32_e32 v141, v88
	v_exp_f32_e32 v150, v89
	v_exp_f32_e32 v142, v90
	v_exp_f32_e32 v149, v91
	v_exp_f32_e32 v143, v92
	v_exp_f32_e32 v148, v93
	v_exp_f32_e32 v144, v94
	v_exp_f32_e32 v147, v95
	v_exp_f32_e32 v145, v96
	v_exp_f32_e32 v146, v97
	v_fmamk_f32 v233, v66, 0x3e38aa3b, v224
	v_fmamk_f32 v234, v67, 0x3e38aa3b, v224
	v_fmamk_f32 v235, v68, 0x3e38aa3b, v224
	v_fmamk_f32 v236, v69, 0x3e38aa3b, v224
	v_fmamk_f32 v237, v70, 0x3e38aa3b, v224
	v_fmamk_f32 v226, v71, 0x3e38aa3b, v224
	v_fmamk_f32 v227, v72, 0x3e38aa3b, v224
	v_fmamk_f32 v228, v73, 0x3e38aa3b, v224
	v_fmamk_f32 v229, v74, 0x3e38aa3b, v224
	v_fmamk_f32 v230, v75, 0x3e38aa3b, v224
	v_fmamk_f32 v231, v76, 0x3e38aa3b, v224
	v_fmamk_f32 v232, v77, 0x3e38aa3b, v224
	v_fmamk_f32 v225, v78, 0x3e38aa3b, v224
	v_fmamk_f32 v238, v79, 0x3e38aa3b, v224
	v_fmamk_f32 v239, v80, 0x3e38aa3b, v224
	v_fmac_f32_e32 v224, 0x3e38aa3b, v81
	s_waitcnt lgkmcnt(0)
	s_barrier
	ds_write_b128 v212, v[114:117]
	ds_write_b128 v213, v[118:121]
	ds_read_b128 v[66:69], v215 offset:32768
	ds_read_b128 v[70:73], v215 offset:36864
	v_exp_f32_e32 v164, v233
	v_exp_f32_e32 v233, v224
	v_add_f32_e32 v224, v153, v138
	s_waitcnt lgkmcnt(1)
	v_mfma_f32_32x32x16_bf16 v[82:97], v[66:69], v[110:113], 0
	v_add_f32_e32 v224, v139, v224
	v_add_f32_e32 v224, v152, v224
	v_add_f32_e32 v224, v140, v224
	ds_read_b128 v[240:243], v216 offset:32768
	ds_read_b128 v[244:247], v216 offset:36864
	v_add_f32_e32 v224, v151, v224
	v_add_f32_e32 v224, v141, v224
	v_add_f32_e32 v224, v150, v224
	s_waitcnt lgkmcnt(2)
	v_mfma_f32_32x32x16_bf16 v[66:81], v[70:73], v[110:113], 0
	v_add_f32_e32 v224, v142, v224
	v_add_f32_e32 v224, v149, v224
	v_add_f32_e32 v224, v143, v224
	v_add_f32_e32 v224, v148, v224
	v_add_f32_e32 v224, v144, v224
	v_exp_f32_e32 v165, v234
	v_add_f32_e32 v224, v147, v224
	s_waitcnt lgkmcnt(1)
	v_mfma_f32_32x32x16_bf16 v[82:97], v[240:243], v[106:109], v[82:97]
	v_exp_f32_e32 v166, v235
	v_add_f32_e32 v224, v145, v224
	v_exp_f32_e32 v167, v236
	v_add_f32_e32 v224, v146, v224
	v_exp_f32_e32 v172, v237
	v_add_f32_e32 v224, v164, v224
	v_exp_f32_e32 v173, v226
	s_waitcnt lgkmcnt(0)
	v_mfma_f32_32x32x16_bf16 v[66:81], v[244:247], v[106:109], v[66:81]
	ds_read_b128 v[240:243], v217 offset:32768
	ds_read_b128 v[244:247], v217 offset:36864
	v_add_f32_e32 v224, v165, v224
	v_exp_f32_e32 v174, v227
	v_add_f32_e32 v224, v166, v224
	v_exp_f32_e32 v175, v228
	v_add_f32_e32 v224, v167, v224
	v_exp_f32_e32 v226, v229
	s_waitcnt lgkmcnt(1)
	v_mfma_f32_32x32x16_bf16 v[82:97], v[240:243], v[102:105], v[82:97]
	v_add_f32_e32 v224, v172, v224
	v_exp_f32_e32 v227, v230
	v_add_f32_e32 v224, v173, v224
	v_exp_f32_e32 v228, v231
	v_add_f32_e32 v224, v174, v224
	v_exp_f32_e32 v229, v232
	v_add_f32_e32 v224, v175, v224
	s_waitcnt lgkmcnt(0)
	v_mfma_f32_32x32x16_bf16 v[66:81], v[244:247], v[102:105], v[66:81]
	ds_read_b128 v[240:243], v218 offset:32768
	ds_read_b128 v[244:247], v218 offset:36864
	v_exp_f32_e32 v230, v225
	v_add_f32_e32 v224, v226, v224
	v_exp_f32_e32 v231, v238
	v_add_f32_e32 v224, v227, v224
	v_exp_f32_e32 v232, v239
	v_add_f32_e32 v224, v228, v224
	s_waitcnt lgkmcnt(1)
	v_mfma_f32_32x32x16_bf16 v[82:97], v[240:243], v[98:101], v[82:97]
	v_add_f32_e32 v224, v229, v224
	v_add_f32_e32 v224, v230, v224
	v_add_f32_e32 v224, v231, v224
	v_add_f32_e32 v224, v232, v224
	v_add_f32_e32 v224, v233, v224
	v_cvt_pk_bf16_f32 v138, v138, v153
	s_waitcnt lgkmcnt(0)
	v_mfma_f32_32x32x16_bf16 v[66:81], v[244:247], v[98:101], v[66:81]
	v_cvt_pk_bf16_f32 v139, v139, v152
	v_cvt_pk_bf16_f32 v140, v140, v151
	v_cvt_pk_bf16_f32 v141, v141, v150
	v_cvt_pk_bf16_f32 v142, v142, v149
	v_cvt_pk_bf16_f32 v143, v143, v148
	v_cvt_pk_bf16_f32 v144, v144, v147
	v_cvt_pk_bf16_f32 v145, v145, v146
	v_cvt_pk_bf16_f32 v146, v164, v165
	v_cvt_pk_bf16_f32 v147, v166, v167
	v_cvt_pk_bf16_f32 v148, v172, v173
	v_cvt_pk_bf16_f32 v149, v174, v175
	v_cvt_pk_bf16_f32 v150, v226, v227
	v_cvt_pk_bf16_f32 v151, v228, v229
	v_cvt_pk_bf16_f32 v152, v230, v231
	v_cvt_pk_bf16_f32 v153, v232, v233
	s_cmp_gt_u32 s8, 60
	s_cselect_b64 s[4:5], -1, 0
	s_and_b64 vcc, exec, s[4:5]
	s_cbranch_vccnz .Lod_d2
	global_load_dwordx4 v[114:117], v[178:179], off offset:2048
	global_load_dwordx4 v[118:121], v[180:181], off offset:2048
	global_load_dwordx4 v[122:125], v[204:205], off offset:1152
	s_mov_b32 s6, 0xa0000
	s_mov_b32 s7, 0
	v_lshl_add_u64 v[178:179], v[178:179], 0, s[6:7]
	v_lshl_add_u64 v[180:181], v[180:181], 0, s[6:7]
	v_lshl_add_u64 v[204:205], v[204:205], 0, s[6:7]

; #define SBAR() __builtin_amdgcn_sched_barrier(0)
; #define SLOAD(i, k0) do { sr_[i].vs0 = *reinterpret_cast<const bf16x8*>(&Vh[(long)((k0) + sr) * LDP + sc]); sr_[i].vs1 = *reinterpret_cast<const bf16x8*>(&Vh[(long)((k0) + 32 + sr) * LDP + sc]); \
;     sr_[i].ks0 = *reinterpret_cast<const bf16x8*>(&Kh[(long)((k0) + ksr) * LDP + ksc]); if (DK == 128) sr_[i].ks1 = *reinterpret_cast<const bf16x8*>(&Kh[(long)((k0) + 32 + ksr) * LDP + ksc]); } while (0)
; #define SWAIT() do { if (SD == 1) asm volatile("s_waitcnt vmcnt(0)" ::: "memory"); else if (DK == 128) asm volatile("s_waitcnt vmcnt(4)" ::: "memory"); else asm volatile("s_waitcnt vmcnt(3)" ::: "memory"); } while (0)
; #define RESC(a) do { if (__any((a) < 1.f)) { if (hi == 0) al_l[r32] = (a); asm volatile("s_waitcnt lgkmcnt(0)" ::: "memory"); \
;     _Pragma("unroll") for (int d = 0; d < 4; ++d) _Pragma("unroll") for (int r = 0; r < 16; ++r) o[d][r] *= al_l[crow(r, hi)]; } } while (0)
; #define HOOK(P0, P1, j) do { if (NA) na_hook(P0, P1, krow0 + (j), q_row, q_col, win_r, win_c, rpb, inv_scale, hi); } while (0)
; __device__ __forceinline__ void partialSM(f32x16& p0, f32x16& p1, float& m_reg, float& mn, float& alpha, float C, float thrRaw) {
;     ...
;   float mnC = -mn * C;
; #pragma unroll
;   for (int r = 0; r < 16; ++r) p0[r] = fmaf(p0[r], C, mnC);
; #pragma unroll
;   for (int r = 0; r < 16; ++r) p1[r] = fmaf(p1[r], C, mnC);
; #pragma unroll
;   for (int r = 0; r < 16; ++r) p0[r] = __builtin_amdgcn_exp2f(p0[r]);
; template <int DK, bool NA, bool QL, int SD> ...
;     ...
;     __syncthreads(); SWAIT(); SWRITE(0, SE);
;     RESC(alB); __syncthreads();
;     SBAR(); qkt<DK, QL>(pA0, pA1, K_lds, qr, ql, r32, hi); HOOK(pA0, pA1, j + 1);
;     finishSM(pB0, pB1, alB, l_reg, pa0, pa1, pa2, pa3); SBAR();
;     if (SD == 1 || j + 3 < NT) SLOAD(SE, (j + 1 + SD) * KVBLK); SBAR();
;     pv_d0(o, vb0 + (int)SHM_V, pa0, pa1, pa2, pa3); partialSM(pA0, pA1, m_reg, mnA, alA, C, thrRaw);
;     __syncthreads(); SWAIT(); SWRITE(1, SO);
;     RESC(alA); __syncthreads();
;   }
.LBB0_711:
	v_cndmask_b32_e64 v142, v138, v223, s[2:3]
	v_mul_f32_e32 v132, 0xbe38aa3b, v142
	s_mov_b32 s2, 0x3e38aa3b
	v_pk_fma_f32 v[82:83], v[82:83], s[2:3], v[132:133] op_sel_hi:[1,0,0]
	v_pk_fma_f32 v[84:85], v[84:85], s[2:3], v[132:133] op_sel_hi:[1,0,0]
	v_pk_fma_f32 v[86:87], v[86:87], s[2:3], v[132:133] op_sel_hi:[1,0,0]
	v_pk_fma_f32 v[88:89], v[88:89], s[2:3], v[132:133] op_sel_hi:[1,0,0]
	v_pk_fma_f32 v[90:91], v[90:91], s[2:3], v[132:133] op_sel_hi:[1,0,0]
	v_pk_fma_f32 v[92:93], v[92:93], s[2:3], v[132:133] op_sel_hi:[1,0,0]
	v_pk_fma_f32 v[94:95], v[94:95], s[2:3], v[132:133] op_sel_hi:[1,0,0]
	v_pk_fma_f32 v[96:97], v[96:97], s[2:3], v[132:133] op_sel_hi:[1,0,0]
	s_mov_b32 s2, 0x3e38aa3b
	v_exp_f32_e32 v177, v82
	v_exp_f32_e32 v226, v83
	v_exp_f32_e32 v161, v84
	v_exp_f32_e32 v223, v85
	v_exp_f32_e32 v153, v86
	v_exp_f32_e32 v176, v87
	v_exp_f32_e32 v152, v88
	v_exp_f32_e32 v160, v89
	v_exp_f32_e32 v149, v90
	v_exp_f32_e32 v151, v91
	v_exp_f32_e32 v147, v92
	v_exp_f32_e32 v150, v93
	v_exp_f32_e32 v145, v94
	v_exp_f32_e32 v148, v95
	v_exp_f32_e32 v144, v96
	v_exp_f32_e32 v146, v97
	v_pk_fma_f32 v[138:139], v[66:67], s[2:3], v[132:133] op_sel_hi:[1,0,0]
	v_pk_fma_f32 v[136:137], v[68:69], s[2:3], v[132:133] op_sel_hi:[1,0,0]
	v_pk_fma_f32 v[130:131], v[70:71], s[2:3], v[132:133] op_sel_hi:[1,0,0]
	v_pk_fma_f32 v[128:129], v[72:73], s[2:3], v[132:133] op_sel_hi:[1,0,0]
	v_pk_fma_f32 v[126:127], v[74:75], s[2:3], v[132:133] op_sel_hi:[1,0,0]
	v_pk_fma_f32 v[140:141], v[76:77], s[2:3], v[132:133] op_sel_hi:[1,0,0]
	v_pk_fma_f32 v[134:135], v[78:79], s[2:3], v[132:133] op_sel_hi:[1,0,0]
	v_pk_fma_f32 v[132:133], v[80:81], s[2:3], v[132:133] op_sel_hi:[1,0,0]
	v_fma_f32 v66, v219, v209, v220
	v_fma_f32 v209, v66, v222, v224
	s_add_i32 s8, s8, 2
	s_and_b64 vcc, exec, s[4:5]
	s_waitcnt lgkmcnt(0)
	s_barrier
	s_cbranch_vccnz .LBB0_713
	v_mov_b32_e32 v219, v143
	ds_write_b128 v212, v[182:185] offset:16384
	ds_write_b128 v213, v[194:197] offset:16384
	s_branch .LBB0_701
